# fox early-exit vote read as two ds_read_b128 instead of eight dependent ds_read_b32+wait steps behind the step barrier
# speedup vs baseline: 1.0106x; 1.0068x over previous
; template<int MODE,int THRL> __device__ __forceinline__ void attn_unit(int b,int h,int qb,const bf16*Q,const bf16*__restrict__ K,const bf16*__restrict__ V,bf16*O,char*shm,const float*__restrict__ cs2,const float*__restrict__ relb,float kmx){
;     ...
;     if constexpr(MODE==0){ if(t>=3){ const unsigned v_=votes[0]&votes[1]&votes[2]&votes[3]&votes[4]&votes[5]&votes[6]&votes[7]; if(__builtin_amdgcn_readfirstlane(v_)!=0u){ early=true; break; } } }
.LBB0_266:
	s_add_i32 s26, s2, 0x2000
	s_cmpk_lg_i32 s2, 0x4000
	s_cselect_b32 s26, s26, 0
	s_andn2_b64 vcc, exec, s[60:61]
	s_cbranch_vccnz .LBB0_268
	v_mov_b32_e32 v0, 0x1c800
	ds_read_b128 v[68:71], v0
	ds_read_b128 v[72:75], v0 offset:16
	s_waitcnt lgkmcnt(0)
	v_and_b32_e32 v0, v68, v69
	v_and_b32_e32 v1, v70, v71
	v_and_b32_e32 v68, v72, v73
	v_and_b32_e32 v69, v74, v75
	v_and_b32_e32 v0, v0, v1
	v_and_b32_e32 v68, v68, v69
	v_and_b32_e32 v0, v0, v68
	s_nop 0
	v_readfirstlane_b32 s33, v0
	s_cmp_eq_u32 s33, 0
	s_cselect_b64 s[58:59], -1, 0
